# hg_prep LDS swizzle: 16-byte groups of the KET / VT rows rotated by (row>>3)%5 (transposed b16 scatters no longer 8-way bank conflicted)
# speedup vs baseline: 1.0136x; 1.0136x over previous
; #define GAS __attribute__((address_space(1)))
; #define LAS __attribute__((address_space(3)))
; #define VM_WAIT() asm volatile("s_waitcnt vmcnt(0)" ::: "memory")
; __device__ __forceinline__ void hg_prep(const Frame& F, unsigned char* ws, unsigned char* sfr) {
;     ...
;     const int tid = F.tid, c = tid >> 4, kg = tid & 15, lane = F.lane, wave = F.wave;
;     for (int u = F.vcu; u < 2048 + NSEQ_S; u += F.G) {
;         int t0, nvalid, h; unsigned char *qf, *vf, *lf; int qp, lp;
;         if (u < 2048) { const int b = u >> 8, n = u & 63; h = (u >> 6) & 3; t0 = b * 2048 + n * 32; nvalid = 32;
;             const size_t e0 = (size_t)t0 * DA + h * 128; qf = ws + WS_Q + e0 * 2; vf = ws + WS_V + e0 * 2; lf = ws + WS_LOGF + e0 * 4; qp = 1024; lp = 2048; }
;         else { const int su = u - 2048, b = su >> 2; h = su & 3; t0 = TP + b * 8; nvalid = 8;
;             unsigned char* base = sfr + (size_t)su * 65536; qf = base; vf = base + 8192; lf = base + 16384; qp = 256; lp = 512; }
;         f32x4 lf0 = {0.f, 0.f, 0.f, 0.f}, lf1 = {0.f, 0.f, 0.f, 0.f}; v4u q8 = {0u, 0u, 0u, 0u}, v8 = {0u, 0u, 0u, 0u};
;         if (c < nvalid) { const size_t e = (size_t)(t0 + c) * DA + h * 128 + 8 * kg;
;             lf0 = NTL((const GAS f32x4*)(LFg + e)); lf1 = NTL((const GAS f32x4*)(LFg + e + 4)); q8 = NTL((const GAS v4u*)(Qg + e)); v8 = NTL((const GAS v4u*)(Vg + e)); }
;         VM_WAIT();
;         *(LAS f32x4*)(LB + c * 132 + 8 * kg) = lf0; *(LAS f32x4*)(LB + c * 132 + 8 * kg + 4) = lf1;
;         { const unsigned vv[4] = {v8.x, v8.y, v8.z, v8.w};
; #pragma unroll
;           for (int j = 0; j < 4; ++j) { VT[(8 * kg + 2 * j) * 40 + c] = (bf16)(vv[j] & 0xffffu); VT[(8 * kg + 2 * j + 1) * 40 + c] = (bf16)(vv[j] >> 16); } }
;     ...
;             const int tt = tid - 256;
; #pragma unroll
;             for (int rep = 0; rep < 2; ++rep) { const int p = tt + 256 * rep, kb = p >> 6, l2 = p & 63, o = p << 4;
;                 const v4u x = *(LAS v4u*)(KET + (16 * kb + (l2 & 15)) * 40 + 8 * (l2 >> 4));
;                 *(GAS v4u*)(lf + (size_t)(o >> 9) * lp + (o & 511)) = x;
;                 const v4u y = *(LAS v4u*)(VT + (16 * kb + (l2 & 15)) * 40 + 8 * (l2 >> 4));
;                 *(GAS v4u*)(vf + (size_t)(o >> 8) * qp + (o & 255)) = y; }
.LBB0_431:
	s_cmpk_gt_i32 s33, 0x9ff
	s_cbranch_scc1 .LBB0_454
	s_add_u32 s3, s20, 0x4608000
	s_addc_u32 s19, s21, 0
	s_add_u32 s36, s22, 0xb980000
	s_addc_u32 s37, s23, 0
	s_add_u32 s38, s22, 0xca80000
	s_addc_u32 s39, s23, 0
	s_add_u32 s40, s22, 0xdb80000
	s_addc_u32 s41, s23, 0
	v_ashrrev_i32_e32 v1, 4, v188
	s_movk_i32 s6, 0x210
	s_cmp_gt_i32 s50, 3
	v_and_b32_e32 v5, 15, v188
	v_mul_lo_u32 v2, v1, s6
	s_cselect_b64 s[44:45], -1, 0
	s_cmp_lg_u32 s50, 1
	v_add_u32_e32 v2, 0, v2
	v_lshlrev_b32_e32 v3, 5, v5
	s_cselect_b64 s[46:47], -1, 0
	s_lshl_b32 s11, s50, 3
	v_add_u32_e32 v23, v2, v3
	v_add_u32_e32 v39, 0, v3
	v_lshlrev_b32_e32 v3, 8, v1
	v_lshlrev_b32_e32 v7, 4, v188
	v_and_b32_e32 v11, 15, v189
	s_and_b32 s12, s11, -16
	v_bfi_b32 v12, -16, s11, v189
	s_movk_i32 s11, 0x110
	s_lshl_b32 s13, s50, 4
	v_sub_u32_e32 v2, v2, v3
	s_movk_i32 s10, 0xfef2
	v_and_b32_e32 v6, 15, v1
	v_and_b32_e32 v8, 0xc0, v7
	v_and_b32_e32 v9, 0xfffff00, v188
	v_mul_lo_u32 v12, v12, s11
	v_and_b32_e32 v13, 48, v189
	v_and_or_b32 v11, s13, 16, v11
	v_lshl_add_u32 v40, v5, 4, v2
	v_mad_u64_u32 v[2:3], s[8:9], v1, s10, v[2:3]
	v_or3_b32 v6, v6, v9, v8
	v_add3_u32 v41, 0, v12, v13
	v_mad_u32_u24 v12, v11, s11, 0
	v_lshlrev_b32_e32 v4, 2, v188
	v_lshlrev_b32_e32 v3, 9, v188
	v_add_u32_e32 v42, v12, v13
	v_lshrrev_b32_e32 v13, 2, v189
	v_mad_i32_i24 v12, v11, s10, v12
	v_lshrrev_b32_e32 v15, 2, v188
	s_mov_b32 s10, 0xffffff0
	v_lshlrev_b32_e32 v6, 4, v6
	s_movk_i32 s11, 0x200
	v_and_b32_e32 v8, 8, v4
	v_add_u32_e32 v9, 0xffffff00, v188
	v_and_or_b32 v13, v13, 12, s12
	v_and_or_b32 v15, v15, s10, v5
	s_movk_i32 s12, 0x50
	v_and_or_b32 v3, v3, s11, v6
	s_movk_i32 s11, 0xf0
	v_and_b32_e32 v10, 48, v188
	v_add_u32_e32 v14, 0x2000, v7
	v_mul_lo_u32 v15, v15, s12
	v_and_or_b32 v28, v6, s11, v8
	v_lshrrev_b32_e32 v6, 2, v9
	v_lshlrev_b32_e32 v22, 3, v5
	v_add_u32_e32 v38, 0, v4
	v_add_u32_e32 v4, 0, v10
	v_add3_u32 v43, 0, v15, v10
	v_ashrrev_i32_e32 v44, 9, v14
	v_mul_u32_u24_e32 v10, 0x280, v5
	v_mul_u32_u24_e32 v14, 0x260, v5
	v_and_or_b32 v5, v6, s10, v5
	v_ashrrev_i32_e32 v46, 8, v3
	v_lshlrev_b32_e32 v3, 4, v9
	v_mad_u64_u32 v[30:31], s[10:11], v5, s12, v[4:5]
	v_add_u32_e32 v49, v4, v15
	v_or_b32_e32 v4, 1, v13
	v_and_b32_e32 v32, 0x1f0, v3
	v_and_b32_e32 v34, 0xf0, v3
	v_mul_lo_u32 v3, v13, s12
	v_cmp_lt_i32_e64 s[12:13], v4, v11
	v_or_b32_e32 v4, 2, v13
	v_mov_b32_e32 v25, 0
	s_movk_i32 s6, 0x80
	v_lshlrev_b32_e32 v16, 1, v1
	v_cmp_lt_i32_e64 s[14:15], v4, v11
	v_or_b32_e32 v4, 3, v13
	s_mov_b32 s43, 0
	v_cmp_gt_i32_e64 s[6:7], s6, v188
	v_cmp_gt_u32_e64 s[8:9], 16, v188
	v_lshlrev_b32_e32 v24, 5, v188
	v_and_b32_e32 v26, 0x1f0, v7
	v_mov_b32_e32 v27, v25
	v_add3_u32 v45, v39, v14, v16
	v_mov_b32_e32 v29, v25
	v_or_b32_e32 v47, 1, v46
	v_bfe_i32 v31, v9, 5, 23
	v_mov_b32_e32 v33, v25
	v_bfe_i32 v48, v9, 4, 24
	v_mov_b32_e32 v35, v25
	v_bfe_i32 v50, v188, 5, 23
	v_bfe_i32 v51, v188, 4, 24
	v_and_b32_e32 v36, 0xf0, v7
	v_mov_b32_e32 v37, v25
	v_cmp_lt_i32_e64 s[10:11], v13, v11
	v_cmp_lt_i32_e64 s[16:17], v4, v11
	s_movk_i32 s62, 0x7fff
	v_add_u32_e32 v52, v2, v10
	v_add_u32_e32 v53, v12, v3
	v_lshrrev_b32_e32 v72, 7, v188
	v_and_b32_e32 v73, 15, v188
	v_add_u32_e32 v74, v72, v73
	v_mul_u32_u24_e32 v75, 13, v74
	v_lshrrev_b32_e32 v75, 6, v75
	v_mul_u32_u24_e32 v75, 5, v75
	v_sub_u32_e32 v74, v74, v75
	v_sub_u32_e32 v74, v74, v72
	v_lshlrev_b32_e32 v74, 4, v74
	v_add_u32_e32 v45, v45, v74
	v_add_u32_e32 v52, v52, v74
	v_bfe_u32 v72, v188, 4, 2
	v_bfe_u32 v73, v188, 3, 1
	v_bfe_u32 v76, v188, 6, 2
	v_lshl_add_u32 v73, v76, 1, v73
	v_add_u32_e32 v74, v72, v73
	v_mul_u32_u24_e32 v75, 13, v74
	v_lshrrev_b32_e32 v75, 6, v75
	v_mul_u32_u24_e32 v75, 5, v75
	v_sub_u32_e32 v74, v74, v75
	v_sub_u32_e32 v74, v74, v72
	v_lshlrev_b32_e32 v74, 4, v74
	v_add_u32_e32 v30, v30, v74
	v_add_u32_e32 v74, 8, v73
	v_add_u32_e32 v74, v72, v74
	v_mul_u32_u24_e32 v75, 13, v74
	v_lshrrev_b32_e32 v75, 6, v75
	v_mul_u32_u24_e32 v75, 5, v75
	v_sub_u32_e32 v74, v74, v75
	v_sub_u32_e32 v74, v74, v72
	v_lshlrev_b32_e32 v74, 4, v74
	v_add_u32_e32 v49, v49, v74
	s_mov_b32 s63, s33
	s_mov_b32 s98, s63
	s_cmpk_gt_i32 s98, 0x7ff
	s_cbranch_scc1 .Lhgpf_smp_a
	s_lshl_b32 s99, s98, 3
	s_and_b32 s99, s99, 0xfffff800
	s_lshl_b32 s100, s98, 5
	s_and_b32 s100, s100, 0x7e0
	s_or_b32 s99, s99, s100
	s_bfe_u32 s100, s98, 0x20006
	s_movk_i32 s101, 32
	s_branch .Lhgpf_go_a
